# row phases k=2,k=6: stores of the last trip are write-through (sc1) so the barrier's L2 write-back has less fresh dirty data
# speedup vs baseline: 1.0209x; 1.0018x over previous
.LBB0_56:
	s_add_i32 s4, s2, 1
	s_cmp_lt_i32 s4, s6
	s_cselect_b64 s[4:5], -1, 0
	s_add_i32 s97, s2, 2
	s_cmp_ge_i32 s97, s6
	s_cselect_b32 s97, 1, 0
	v_cndmask_b32_e64 v64, 0, 1, s[4:5]
	v_mov_b32_e32 v65, s59
	v_add_co_u32_e32 v128, vcc, 0x2000000, v94
	v_lshl_add_u64 v[64:65], v[64:65], 0, s[2:3]
	s_nop 0
	v_addc_co_u32_e32 v129, vcc, 0, v95, vcc
	v_lshl_add_u64 v[64:65], v[64:65], 0, v[72:73]
	global_load_dwordx4 v[100:103], v[128:129], off
	global_load_dwordx4 v[104:107], v[128:129], off offset:1024
	global_load_dwordx4 v[116:119], v[94:95], off
	global_load_dwordx4 v[120:123], v[94:95], off offset:1024
	v_lshlrev_b64 v[64:65], 11, v[64:65]
	v_lshl_add_u64 v[98:99], v[90:91], 0, v[64:65]
	v_lshl_add_u64 v[96:97], v[92:93], 0, v[64:65]
	global_load_dwordx4 v[108:111], v[98:99], off
	global_load_dwordx4 v[124:127], v[98:99], off offset:1024
	global_load_dwordx4 v[68:71], v[96:97], off
	global_load_dwordx4 v[64:67], v[96:97], off offset:1024
	s_waitcnt vmcnt(7)
	v_lshlrev_b32_e32 v130, 16, v100
	v_and_b32_e32 v131, 0xffff0000, v100
	v_lshlrev_b32_e32 v150, 16, v101
	v_and_b32_e32 v151, 0xffff0000, v101
	v_lshlrev_b32_e32 v152, 16, v102
	v_and_b32_e32 v153, 0xffff0000, v102
	v_lshlrev_b32_e32 v154, 16, v103
	v_and_b32_e32 v155, 0xffff0000, v103
	s_waitcnt vmcnt(2)
	v_lshlrev_b32_e32 v100, 16, v126
	v_and_b32_e32 v101, 0xffff0000, v126
	v_lshlrev_b32_e32 v102, 16, v127
	v_and_b32_e32 v103, 0xffff0000, v127
	v_and_b32_e32 v127, 0xffff0000, v118
	v_and_b32_e32 v126, 0xffff0000, v116
	v_lshlrev_b32_e32 v156, 16, v104
	v_and_b32_e32 v157, 0xffff0000, v104
	v_lshlrev_b32_e32 v158, 16, v105
	v_and_b32_e32 v159, 0xffff0000, v105
	v_lshlrev_b32_e32 v160, 16, v106
	v_and_b32_e32 v161, 0xffff0000, v106
	v_lshlrev_b32_e32 v162, 16, v107
	v_and_b32_e32 v163, 0xffff0000, v107
	v_lshlrev_b32_e32 v104, 16, v124
	v_and_b32_e32 v105, 0xffff0000, v124
	v_lshlrev_b32_e32 v106, 16, v125
	v_and_b32_e32 v107, 0xffff0000, v125
	v_lshlrev_b32_e32 v125, 16, v118
	v_lshlrev_b32_e32 v124, 16, v116
	v_lshlrev_b32_e32 v164, 16, v117
	v_and_b32_e32 v118, 0xffff0000, v117
	v_pk_mul_f32 v[116:117], v[126:127], v[126:127]
	v_and_b32_e32 v169, 0xffff0000, v120
	v_and_b32_e32 v168, 0xffff0000, v122
	v_lshlrev_b32_e32 v165, 16, v119
	v_pk_fma_f32 v[116:117], v[124:125], v[124:125], v[116:117]
	v_lshlrev_b32_e32 v167, 16, v120
	v_lshlrev_b32_e32 v166, 16, v122
	v_lshlrev_b32_e32 v170, 16, v123
	v_and_b32_e32 v120, 0xffff0000, v123
	v_pk_mul_f32 v[122:123], v[168:169], v[168:169]
	v_and_b32_e32 v119, 0xffff0000, v119
	v_pk_fma_f32 v[116:117], v[164:165], v[164:165], v[116:117]
	v_lshlrev_b32_e32 v171, 16, v121
	v_pk_fma_f32 v[122:123], v[166:167], v[166:167], v[122:123]
	v_pk_fma_f32 v[116:117], v[118:119], v[118:119], v[116:117]
	v_and_b32_e32 v121, 0xffff0000, v121
	v_pk_fma_f32 v[122:123], v[170:171], v[170:171], v[122:123]
	v_add_f32_e32 v116, v116, v117
	v_pk_fma_f32 v[122:123], v[120:121], v[120:121], v[122:123]
	v_mov_b32_e32 v173, v126
	v_add_f32_e32 v116, v116, v123
	v_add_f32_e32 v116, v122, v116
	v_mov_b32_e32 v123, v118
	v_mov_b32_e32 v118, v165
	v_add_f32_dpp v116, v116, v116 quad_perm:[1,0,3,2] row_mask:0xf bank_mask:0xf bound_ctrl:1
	v_mov_b32_e32 v126, v125
	v_mov_b32_e32 v122, v164
	v_add_f32_dpp v116, v116, v116 quad_perm:[2,3,0,1] row_mask:0xf bank_mask:0xf bound_ctrl:1
	v_mov_b32_e32 v172, v124
	v_lshlrev_b32_e32 v114, 16, v109
	v_add_f32_dpp v116, v116, v116 row_half_mirror row_mask:0xf bank_mask:0xf bound_ctrl:1
	v_and_b32_e32 v115, 0xffff0000, v109
	v_lshlrev_b32_e32 v112, 16, v108
	v_add_f32_dpp v116, v116, v116 row_mirror row_mask:0xf bank_mask:0xf bound_ctrl:1
	v_and_b32_e32 v113, 0xffff0000, v108
	v_readlane_b32 s7, v116, 16
	v_readlane_b32 s8, v116, 48
	v_readlane_b32 s4, v116, 0
	v_readlane_b32 s5, v116, 32
	v_mov_b32_e32 v116, s7
	v_mov_b32_e32 v117, s8
	v_pk_add_f32 v[116:117], s[4:5], v[116:117]
	v_lshlrev_b32_e32 v108, 16, v110
	v_add_f32_e32 v116, v116, v117
	v_fmamk_f32 v116, v116, 0x3a800000, v137
	v_cmp_gt_f32_e32 vcc, s94, v116
	v_mul_f32_e32 v117, 0x4b800000, v116
	v_and_b32_e32 v109, 0xffff0000, v110
	v_cndmask_b32_e32 v116, v116, v117, vcc
	v_rsq_f32_e32 v116, v116
	v_lshlrev_b32_e32 v110, 16, v111
	v_and_b32_e32 v111, 0xffff0000, v111
	v_mul_f32_e32 v117, 0x45800000, v116
	v_cndmask_b32_e32 v116, v116, v117, vcc
	v_pk_mul_f32 v[118:119], v[116:117], v[118:119] op_sel_hi:[0,1]
	v_pk_mul_f32 v[118:119], v[10:11], v[118:119]
	v_pk_mul_f32 v[124:125], v[116:117], v[126:127] op_sel_hi:[0,1]
	v_pk_fma_f32 v[126:127], v[2:3], v[118:119], v[154:155]
	v_mov_b32_e32 v118, v171
	v_mov_b32_e32 v119, v121
	v_pk_mul_f32 v[122:123], v[116:117], v[122:123] op_sel_hi:[0,1]
	v_pk_mul_f32 v[118:119], v[116:117], v[118:119] op_sel_hi:[0,1]
	v_pk_mul_f32 v[122:123], v[14:15], v[122:123]
	v_pk_mul_f32 v[124:125], v[8:9], v[124:125]
	v_pk_mul_f32 v[118:119], v[30:31], v[118:119]
	v_mov_b32_e32 v171, v120
	v_pk_fma_f32 v[122:123], v[6:7], v[122:123], v[150:151]
	v_pk_fma_f32 v[124:125], v[0:1], v[124:125], v[152:153]
	v_mov_b32_e32 v150, v167
	v_mov_b32_e32 v151, v169
	v_pk_fma_f32 v[152:153], v[22:23], v[118:119], v[158:159]
	v_pk_mul_f32 v[118:119], v[116:117], v[170:171] op_sel_hi:[0,1]
	v_mov_b32_e32 v167, v168
	v_pk_mul_f32 v[172:173], v[116:117], v[172:173] op_sel_hi:[0,1]
	v_pk_mul_f32 v[150:151], v[116:117], v[150:151] op_sel_hi:[0,1]
	v_pk_mul_f32 v[116:117], v[116:117], v[166:167] op_sel_hi:[0,1]
	v_pk_mul_f32 v[118:119], v[26:27], v[118:119]
	v_pk_mul_f32 v[172:173], v[12:13], v[172:173]
	v_pk_mul_f32 v[116:117], v[24:25], v[116:117]
	v_pk_fma_f32 v[120:121], v[18:19], v[118:119], v[162:163]
	v_cvt_pk_bf16_f32 v118, v124, v125
	v_cvt_pk_bf16_f32 v119, v126, v127
	v_pk_fma_f32 v[130:131], v[4:5], v[172:173], v[130:131]
	v_pk_mul_f32 v[150:151], v[28:29], v[150:151]
	v_pk_fma_f32 v[154:155], v[16:17], v[116:117], v[160:161]
	v_cvt_pk_bf16_f32 v116, v130, v131
	v_cvt_pk_bf16_f32 v117, v122, v123
	s_cmp_lg_u32 s97, 0
	s_cbranch_scc1 .Lr56_sc1_0
	global_store_dwordx4 v[128:129], v[116:119], off
	s_branch .Lr56_done_0
.Lr56_sc1_0:
	global_store_dwordx4 v[128:129], v[116:119], off sc1
.Lr56_done_0:
	v_pk_fma_f32 v[150:151], v[20:21], v[150:151], v[156:157]
	v_cvt_pk_bf16_f32 v118, v154, v155
	v_cvt_pk_bf16_f32 v119, v120, v121
	v_cvt_pk_bf16_f32 v116, v150, v151
	v_cvt_pk_bf16_f32 v117, v152, v153
	s_cmp_lg_u32 s97, 0
	s_cbranch_scc1 .Lr56_sc1_1
	global_store_dwordx4 v[128:129], v[116:119], off offset:1024
	s_branch .Lr56_done_1
.Lr56_sc1_1:
	global_store_dwordx4 v[128:129], v[116:119], off offset:1024 sc1
.Lr56_done_1:
	v_mov_b32_e32 v128, v155
	v_mov_b32_e32 v129, v151
	v_mov_b32_e32 v118, v131
	v_mov_b32_e32 v119, v125
	v_mov_b32_e32 v116, v130
	v_mov_b32_e32 v117, v124
	v_pk_mul_f32 v[118:119], v[118:119], v[118:119]
	v_pk_mul_f32 v[128:129], v[128:129], v[128:129]
	v_pk_fma_f32 v[116:117], v[116:117], v[116:117], v[118:119]
	v_mov_b32_e32 v118, v122
	v_mov_b32_e32 v119, v126
	v_pk_fma_f32 v[116:117], v[118:119], v[118:119], v[116:117]
	v_mov_b32_e32 v118, v123
	v_mov_b32_e32 v119, v127
	v_pk_fma_f32 v[116:117], v[118:119], v[118:119], v[116:117]
	v_mov_b32_e32 v118, v154
	v_mov_b32_e32 v119, v150
	v_pk_fma_f32 v[118:119], v[118:119], v[118:119], v[128:129]
	v_mov_b32_e32 v128, v120
	v_mov_b32_e32 v129, v152
	v_pk_fma_f32 v[118:119], v[128:129], v[128:129], v[118:119]
	v_mov_b32_e32 v128, v121
	v_mov_b32_e32 v129, v153
	v_pk_fma_f32 v[118:119], v[128:129], v[128:129], v[118:119]
	v_add_f32_e32 v116, v116, v117
	v_add_f32_e32 v116, v119, v116
	v_add_f32_e32 v116, v118, v116
	s_nop 0
	v_add_f32_dpp v116, v116, v116 quad_perm:[1,0,3,2] row_mask:0xf bank_mask:0xf bound_ctrl:1
	s_nop 1
	v_add_f32_dpp v116, v116, v116 quad_perm:[2,3,0,1] row_mask:0xf bank_mask:0xf bound_ctrl:1
	s_nop 1
	v_add_f32_dpp v116, v116, v116 row_half_mirror row_mask:0xf bank_mask:0xf bound_ctrl:1
	s_nop 1
	v_add_f32_dpp v116, v116, v116 row_mirror row_mask:0xf bank_mask:0xf bound_ctrl:1
	s_nop 0
	v_readlane_b32 s7, v116, 16
	v_readlane_b32 s8, v116, 48
	v_readlane_b32 s4, v116, 0
	v_readlane_b32 s5, v116, 32
	v_mov_b32_e32 v116, s7
	v_mov_b32_e32 v117, s8
	v_pk_add_f32 v[116:117], s[4:5], v[116:117]
	s_nop 0
	v_add_f32_e32 v116, v116, v117
	v_fmamk_f32 v116, v116, 0x3a800000, v137
	v_cmp_gt_f32_e32 vcc, s94, v116
	v_mul_f32_e32 v117, 0x4b800000, v116
	s_nop 0
	v_cndmask_b32_e32 v116, v116, v117, vcc
	v_rsq_f32_e32 v116, v116
	s_nop 0
	v_mul_f32_e32 v117, 0x45800000, v116
	v_cndmask_b32_e32 v116, v116, v117, vcc
	v_pk_mul_f32 v[118:119], v[122:123], v[116:117] op_sel_hi:[1,0]
	v_pk_mul_f32 v[122:123], v[130:131], v[116:117] op_sel_hi:[1,0]
	v_pk_mul_f32 v[118:119], v[46:47], v[118:119]
	v_pk_mul_f32 v[126:127], v[126:127], v[116:117] op_sel_hi:[1,0]
	v_pk_mul_f32 v[124:125], v[124:125], v[116:117] op_sel_hi:[1,0]
	v_pk_mul_f32 v[128:129], v[152:153], v[116:117] op_sel_hi:[1,0]
	v_pk_mul_f32 v[130:131], v[150:151], v[116:117] op_sel_hi:[1,0]
	v_pk_mul_f32 v[120:121], v[120:121], v[116:117] op_sel_hi:[1,0]
	v_pk_mul_f32 v[116:117], v[154:155], v[116:117] op_sel_hi:[1,0]
	v_pk_fma_f32 v[118:119], v[74:75], v[118:119], v[38:39]
	v_pk_mul_f32 v[124:125], v[40:41], v[124:125]
	v_pk_mul_f32 v[126:127], v[42:43], v[126:127]
	v_pk_mul_f32 v[116:117], v[56:57], v[116:117]
	v_pk_mul_f32 v[122:123], v[44:45], v[122:123]
	v_pk_fma_f32 v[126:127], v[78:79], v[126:127], v[34:35]
	v_pk_fma_f32 v[124:125], v[80:81], v[124:125], v[32:33]
	v_pk_mul_f32 v[120:121], v[58:59], v[120:121]
	v_pk_fma_f32 v[150:151], v[88:89], v[116:117], v[48:49]
	v_cvt_pk_bf16_f32 v117, v118, v119
	v_cvt_pk_bf16_f32 v118, v124, v125
	v_cvt_pk_bf16_f32 v119, v126, v127
	v_pk_fma_f32 v[122:123], v[76:77], v[122:123], v[36:37]
	v_pk_mul_f32 v[130:131], v[60:61], v[130:131]
	v_pk_mul_f32 v[128:129], v[62:63], v[128:129]
	v_pk_fma_f32 v[120:121], v[86:87], v[120:121], v[50:51]
	v_cvt_pk_bf16_f32 v116, v122, v123
	s_cmp_lg_u32 s97, 0
	s_cbranch_scc1 .Lr56_sc1_2
	global_store_dwordx4 v[94:95], v[116:119], off
	s_branch .Lr56_done_2
.Lr56_sc1_2:
	global_store_dwordx4 v[94:95], v[116:119], off sc1
.Lr56_done_2:
	v_pk_fma_f32 v[128:129], v[82:83], v[128:129], v[54:55]
	v_pk_fma_f32 v[130:131], v[84:85], v[130:131], v[52:53]
	v_cvt_pk_bf16_f32 v118, v150, v151
	v_cvt_pk_bf16_f32 v119, v120, v121
	v_cvt_pk_bf16_f32 v117, v128, v129
	s_waitcnt vmcnt(4)
	v_lshlrev_b32_e32 v120, 16, v69
	v_cvt_pk_bf16_f32 v116, v130, v131
	s_cmp_lg_u32 s97, 0
	s_cbranch_scc1 .Lr56_sc1_3
	global_store_dwordx4 v[94:95], v[116:119], off offset:1024
	s_branch .Lr56_done_3
.Lr56_sc1_3:
	global_store_dwordx4 v[94:95], v[116:119], off offset:1024 sc1
.Lr56_done_3:
	s_waitcnt vmcnt(4)
	v_and_b32_e32 v125, 0xffff0000, v64
	v_and_b32_e32 v124, 0xffff0000, v66
	v_and_b32_e32 v119, 0xffff0000, v70
	v_and_b32_e32 v118, 0xffff0000, v68
	v_lshlrev_b32_e32 v117, 16, v70
	v_lshlrev_b32_e32 v116, 16, v68
	v_and_b32_e32 v70, 0xffff0000, v69
	v_pk_mul_f32 v[68:69], v[118:119], v[118:119]
	v_lshlrev_b32_e32 v121, 16, v71
	v_pk_fma_f32 v[68:69], v[116:117], v[116:117], v[68:69]
	v_lshlrev_b32_e32 v123, 16, v64
	v_lshlrev_b32_e32 v122, 16, v66
	v_lshlrev_b32_e32 v126, 16, v67
	v_and_b32_e32 v64, 0xffff0000, v67
	v_pk_mul_f32 v[66:67], v[124:125], v[124:125]
	v_and_b32_e32 v71, 0xffff0000, v71
	v_pk_fma_f32 v[68:69], v[120:121], v[120:121], v[68:69]
	v_lshlrev_b32_e32 v127, 16, v65
	v_pk_fma_f32 v[66:67], v[122:123], v[122:123], v[66:67]
	v_pk_fma_f32 v[68:69], v[70:71], v[70:71], v[68:69]
	v_and_b32_e32 v65, 0xffff0000, v65
	v_pk_fma_f32 v[66:67], v[126:127], v[126:127], v[66:67]
	v_add_f32_e32 v68, v68, v69
	v_pk_fma_f32 v[66:67], v[64:65], v[64:65], v[66:67]
	v_mov_b32_e32 v69, v70
	v_add_f32_e32 v67, v68, v67
	v_add_f32_e32 v66, v66, v67
	v_mov_b32_e32 v68, v120
	v_mov_b32_e32 v129, v118
	v_add_f32_dpp v66, v66, v66 quad_perm:[1,0,3,2] row_mask:0xf bank_mask:0xf bound_ctrl:1
	v_mov_b32_e32 v70, v121
	v_mov_b32_e32 v118, v117
	v_add_f32_dpp v66, v66, v66 quad_perm:[2,3,0,1] row_mask:0xf bank_mask:0xf bound_ctrl:1
	v_mov_b32_e32 v128, v116
	v_lshl_add_u64 v[94:95], v[94:95], 0, s[30:31]
	v_add_f32_dpp v66, v66, v66 row_half_mirror row_mask:0xf bank_mask:0xf bound_ctrl:1
	s_nop 1
	v_add_f32_dpp v66, v66, v66 row_mirror row_mask:0xf bank_mask:0xf bound_ctrl:1
	s_nop 0
	v_readlane_b32 s7, v66, 16
	v_readlane_b32 s8, v66, 48
	v_readlane_b32 s4, v66, 0
	v_readlane_b32 s5, v66, 32
	v_mov_b32_e32 v66, s7
	v_mov_b32_e32 v67, s8
	v_pk_add_f32 v[66:67], s[4:5], v[66:67]
	s_nop 0
	v_add_f32_e32 v66, v66, v67
	v_fmamk_f32 v66, v66, 0x3a800000, v137
	v_cmp_gt_f32_e32 vcc, s94, v66
	v_mul_f32_e32 v67, 0x4b800000, v66
	s_nop 0
	v_cndmask_b32_e32 v66, v66, v67, vcc
	v_rsq_f32_e32 v66, v66
	s_nop 0
	v_mul_f32_e32 v67, 0x45800000, v66
	v_cndmask_b32_e32 v66, v66, v67, vcc
	v_pk_mul_f32 v[68:69], v[66:67], v[68:69] op_sel_hi:[0,1]
	v_pk_mul_f32 v[68:69], v[14:15], v[68:69]
	v_pk_mul_f32 v[70:71], v[66:67], v[70:71] op_sel_hi:[0,1]
	v_pk_fma_f32 v[68:69], v[6:7], v[68:69], v[114:115]
	v_pk_mul_f32 v[114:115], v[66:67], v[118:119] op_sel_hi:[0,1]
	v_pk_mul_f32 v[114:115], v[8:9], v[114:115]
	v_pk_mul_f32 v[70:71], v[10:11], v[70:71]
	v_pk_fma_f32 v[108:109], v[0:1], v[114:115], v[108:109]
	v_pk_fma_f32 v[70:71], v[2:3], v[70:71], v[110:111]
	v_mov_b32_e32 v110, v127
	v_mov_b32_e32 v111, v65
	v_mov_b32_e32 v114, v123
	v_mov_b32_e32 v115, v125
	v_mov_b32_e32 v127, v64
	v_mov_b32_e32 v123, v124
	v_pk_mul_f32 v[128:129], v[66:67], v[128:129] op_sel_hi:[0,1]
	v_pk_mul_f32 v[110:111], v[66:67], v[110:111] op_sel_hi:[0,1]
	v_pk_mul_f32 v[114:115], v[66:67], v[114:115] op_sel_hi:[0,1]
	v_pk_mul_f32 v[64:65], v[66:67], v[126:127] op_sel_hi:[0,1]
	v_pk_mul_f32 v[66:67], v[66:67], v[122:123] op_sel_hi:[0,1]
	v_pk_mul_f32 v[66:67], v[24:25], v[66:67]
	v_pk_mul_f32 v[128:129], v[12:13], v[128:129]
	v_pk_mul_f32 v[64:65], v[26:27], v[64:65]
	v_pk_fma_f32 v[100:101], v[16:17], v[66:67], v[100:101]
	v_cvt_pk_bf16_f32 v66, v108, v109
	v_cvt_pk_bf16_f32 v67, v70, v71
	v_pk_fma_f32 v[112:113], v[4:5], v[128:129], v[112:113]
	v_pk_mul_f32 v[114:115], v[28:29], v[114:115]
	v_pk_mul_f32 v[110:111], v[30:31], v[110:111]
	v_pk_fma_f32 v[102:103], v[18:19], v[64:65], v[102:103]
	v_cvt_pk_bf16_f32 v64, v112, v113
	v_cvt_pk_bf16_f32 v65, v68, v69
	s_cmp_lg_u32 s97, 0
	s_cbranch_scc1 .Lr56_sc1_4
	global_store_dwordx4 v[98:99], v[64:67], off
	s_branch .Lr56_done_4
.Lr56_sc1_4:
	global_store_dwordx4 v[98:99], v[64:67], off sc1
.Lr56_done_4:
	v_pk_fma_f32 v[106:107], v[22:23], v[110:111], v[106:107]
	v_pk_fma_f32 v[104:105], v[20:21], v[114:115], v[104:105]
	v_cvt_pk_bf16_f32 v66, v100, v101
	v_cvt_pk_bf16_f32 v67, v102, v103
	v_cvt_pk_bf16_f32 v65, v106, v107
	s_nop 0
	v_cvt_pk_bf16_f32 v64, v104, v105
	s_cmp_lg_u32 s97, 0
	s_cbranch_scc1 .Lr56_sc1_5
	global_store_dwordx4 v[98:99], v[64:67], off offset:1024
	s_branch .Lr56_done_5
.Lr56_sc1_5:
	global_store_dwordx4 v[98:99], v[64:67], off offset:1024 sc1
.Lr56_done_5:
	v_mov_b32_e32 v98, v101
	v_mov_b32_e32 v99, v105
	v_mov_b32_e32 v66, v113
	v_mov_b32_e32 v67, v109
	v_mov_b32_e32 v64, v112
	v_mov_b32_e32 v65, v108
	v_pk_mul_f32 v[66:67], v[66:67], v[66:67]
	v_pk_mul_f32 v[98:99], v[98:99], v[98:99]
	v_pk_fma_f32 v[64:65], v[64:65], v[64:65], v[66:67]
	v_mov_b32_e32 v66, v68
	v_mov_b32_e32 v67, v70
	v_pk_fma_f32 v[64:65], v[66:67], v[66:67], v[64:65]
	v_mov_b32_e32 v66, v69
	v_mov_b32_e32 v67, v71
	v_pk_fma_f32 v[64:65], v[66:67], v[66:67], v[64:65]
	v_mov_b32_e32 v66, v100
	v_mov_b32_e32 v67, v104
	v_pk_fma_f32 v[66:67], v[66:67], v[66:67], v[98:99]
	v_mov_b32_e32 v98, v102
	v_mov_b32_e32 v99, v106
	v_pk_fma_f32 v[66:67], v[98:99], v[98:99], v[66:67]
	v_mov_b32_e32 v98, v103
	v_mov_b32_e32 v99, v107
	v_pk_fma_f32 v[66:67], v[98:99], v[98:99], v[66:67]
	v_add_f32_e32 v64, v64, v65
	v_add_f32_e32 v64, v67, v64
	v_add_f32_e32 v64, v66, v64
	s_nop 1
	v_add_f32_dpp v64, v64, v64 quad_perm:[1,0,3,2] row_mask:0xf bank_mask:0xf bound_ctrl:1
	s_nop 1
	v_add_f32_dpp v64, v64, v64 quad_perm:[2,3,0,1] row_mask:0xf bank_mask:0xf bound_ctrl:1
	s_nop 1
	v_add_f32_dpp v64, v64, v64 row_half_mirror row_mask:0xf bank_mask:0xf bound_ctrl:1
	s_nop 1
	v_add_f32_dpp v64, v64, v64 row_mirror row_mask:0xf bank_mask:0xf bound_ctrl:1
	s_nop 0
	v_readlane_b32 s7, v64, 16
	v_readlane_b32 s8, v64, 48
	v_readlane_b32 s4, v64, 0
	v_readlane_b32 s5, v64, 32
	v_mov_b32_e32 v64, s7
	v_mov_b32_e32 v65, s8
	v_pk_add_f32 v[64:65], s[4:5], v[64:65]
	s_nop 0
	v_add_f32_e32 v64, v64, v65
	v_fmamk_f32 v64, v64, 0x3a800000, v137
	v_cmp_gt_f32_e32 vcc, s94, v64
	v_mul_f32_e32 v65, 0x4b800000, v64
	s_nop 0
	v_cndmask_b32_e32 v64, v64, v65, vcc
	v_rsq_f32_e32 v64, v64
	s_nop 0
	v_mul_f32_e32 v65, 0x45800000, v64
	v_cndmask_b32_e32 v64, v64, v65, vcc
	v_pk_mul_f32 v[66:67], v[68:69], v[64:65] op_sel_hi:[1,0]
	v_pk_mul_f32 v[68:69], v[112:113], v[64:65] op_sel_hi:[1,0]
	v_pk_mul_f32 v[66:67], v[46:47], v[66:67]
	v_pk_mul_f32 v[70:71], v[70:71], v[64:65] op_sel_hi:[1,0]
	v_pk_mul_f32 v[98:99], v[108:109], v[64:65] op_sel_hi:[1,0]
	v_pk_mul_f32 v[106:107], v[106:107], v[64:65] op_sel_hi:[1,0]
	v_pk_mul_f32 v[104:105], v[104:105], v[64:65] op_sel_hi:[1,0]
	v_pk_mul_f32 v[102:103], v[102:103], v[64:65] op_sel_hi:[1,0]
	v_pk_mul_f32 v[64:65], v[100:101], v[64:65] op_sel_hi:[1,0]
	v_pk_mul_f32 v[68:69], v[44:45], v[68:69]
	v_pk_fma_f32 v[66:67], v[74:75], v[66:67], v[38:39]
	v_pk_mul_f32 v[98:99], v[40:41], v[98:99]
	v_pk_mul_f32 v[70:71], v[42:43], v[70:71]
	v_pk_mul_f32 v[64:65], v[56:57], v[64:65]
	v_pk_fma_f32 v[68:69], v[76:77], v[68:69], v[36:37]
	v_pk_fma_f32 v[70:71], v[78:79], v[70:71], v[34:35]
	v_pk_fma_f32 v[98:99], v[80:81], v[98:99], v[32:33]
	v_pk_mul_f32 v[104:105], v[60:61], v[104:105]
	v_pk_mul_f32 v[106:107], v[62:63], v[106:107]
	v_pk_mul_f32 v[100:101], v[58:59], v[102:103]
	v_pk_fma_f32 v[102:103], v[88:89], v[64:65], v[48:49]
	v_cvt_pk_bf16_f32 v64, v68, v69
	v_cvt_pk_bf16_f32 v65, v66, v67
	v_cvt_pk_bf16_f32 v66, v98, v99
	v_cvt_pk_bf16_f32 v67, v70, v71
	v_pk_fma_f32 v[106:107], v[82:83], v[106:107], v[54:55]
	v_pk_fma_f32 v[104:105], v[84:85], v[104:105], v[52:53]
	v_pk_fma_f32 v[100:101], v[86:87], v[100:101], v[50:51]
	s_cmp_lg_u32 s97, 0
	s_cbranch_scc1 .Lr56_sc1_6
	global_store_dwordx4 v[96:97], v[64:67], off
	s_branch .Lr56_done_6
.Lr56_sc1_6:
	global_store_dwordx4 v[96:97], v[64:67], off sc1
.Lr56_done_6:
	s_nop 1
	v_cvt_pk_bf16_f32 v64, v104, v105
	v_cvt_pk_bf16_f32 v65, v106, v107
	v_cvt_pk_bf16_f32 v66, v102, v103
	v_cvt_pk_bf16_f32 v67, v100, v101
	s_cmp_lg_u32 s97, 0
	s_cbranch_scc1 .Lr56_sc1_7
	global_store_dwordx4 v[96:97], v[64:67], off offset:1024
	s_branch .Lr56_done_7
.Lr56_sc1_7:
	global_store_dwordx4 v[96:97], v[64:67], off offset:1024 sc1
.Lr56_done_7:
	s_add_u32 s2, s2, 2
	s_addc_u32 s3, s3, 0
	s_cmp_ge_i32 s2, s6
	s_cbranch_scc0 .LBB0_56

.LBB0_1086:
	s_add_i32 s4, s2, 1
	s_cmp_lt_i32 s4, s8
	s_cselect_b64 s[4:5], -1, 0
	s_add_i32 s97, s2, 2
	s_cmp_ge_i32 s97, s8
	s_cselect_b32 s97, 1, 0
	v_cndmask_b32_e64 v48, 0, 1, s[4:5]
	v_mov_b32_e32 v49, s59
	v_add_co_u32_e32 v128, vcc, 0x2000000, v94
	v_lshl_add_u64 v[48:49], v[48:49], 0, s[2:3]
	s_nop 0
	v_addc_co_u32_e32 v129, vcc, 0, v95, vcc
	v_lshl_add_u64 v[48:49], v[48:49], 0, v[56:57]
	global_load_dwordx4 v[100:103], v[128:129], off
	global_load_dwordx4 v[104:107], v[128:129], off offset:1024
	global_load_dwordx4 v[116:119], v[94:95], off
	global_load_dwordx4 v[120:123], v[94:95], off offset:1024
	v_lshlrev_b64 v[48:49], 11, v[48:49]
	v_lshl_add_u64 v[98:99], v[90:91], 0, v[48:49]
	v_lshl_add_u64 v[96:97], v[92:93], 0, v[48:49]
	global_load_dwordx4 v[108:111], v[98:99], off
	global_load_dwordx4 v[124:127], v[98:99], off offset:1024
	global_load_dwordx4 v[52:55], v[96:97], off
	global_load_dwordx4 v[48:51], v[96:97], off offset:1024
	s_waitcnt vmcnt(7)
	v_lshlrev_b32_e32 v130, 16, v100
	v_and_b32_e32 v131, 0xffff0000, v100
	v_lshlrev_b32_e32 v150, 16, v101
	v_and_b32_e32 v151, 0xffff0000, v101
	v_lshlrev_b32_e32 v152, 16, v102
	v_and_b32_e32 v153, 0xffff0000, v102
	v_lshlrev_b32_e32 v154, 16, v103
	v_and_b32_e32 v155, 0xffff0000, v103
	s_waitcnt vmcnt(2)
	v_lshlrev_b32_e32 v100, 16, v126
	v_and_b32_e32 v101, 0xffff0000, v126
	v_lshlrev_b32_e32 v102, 16, v127
	v_and_b32_e32 v103, 0xffff0000, v127
	v_and_b32_e32 v127, 0xffff0000, v118
	v_and_b32_e32 v126, 0xffff0000, v116
	v_lshlrev_b32_e32 v156, 16, v104
	v_and_b32_e32 v157, 0xffff0000, v104
	v_lshlrev_b32_e32 v158, 16, v105
	v_and_b32_e32 v159, 0xffff0000, v105
	v_lshlrev_b32_e32 v160, 16, v106
	v_and_b32_e32 v161, 0xffff0000, v106
	v_lshlrev_b32_e32 v162, 16, v107
	v_and_b32_e32 v163, 0xffff0000, v107
	v_lshlrev_b32_e32 v104, 16, v124
	v_and_b32_e32 v105, 0xffff0000, v124
	v_lshlrev_b32_e32 v106, 16, v125
	v_and_b32_e32 v107, 0xffff0000, v125
	v_lshlrev_b32_e32 v125, 16, v118
	v_lshlrev_b32_e32 v124, 16, v116
	v_lshlrev_b32_e32 v164, 16, v117
	v_and_b32_e32 v118, 0xffff0000, v117
	v_pk_mul_f32 v[116:117], v[126:127], v[126:127]
	v_and_b32_e32 v169, 0xffff0000, v120
	v_and_b32_e32 v168, 0xffff0000, v122
	v_lshlrev_b32_e32 v165, 16, v119
	v_pk_fma_f32 v[116:117], v[124:125], v[124:125], v[116:117]
	v_lshlrev_b32_e32 v167, 16, v120
	v_lshlrev_b32_e32 v166, 16, v122
	v_lshlrev_b32_e32 v170, 16, v123
	v_and_b32_e32 v120, 0xffff0000, v123
	v_pk_mul_f32 v[122:123], v[168:169], v[168:169]
	v_and_b32_e32 v119, 0xffff0000, v119
	v_pk_fma_f32 v[116:117], v[164:165], v[164:165], v[116:117]
	v_lshlrev_b32_e32 v171, 16, v121
	v_pk_fma_f32 v[122:123], v[166:167], v[166:167], v[122:123]
	v_pk_fma_f32 v[116:117], v[118:119], v[118:119], v[116:117]
	v_and_b32_e32 v121, 0xffff0000, v121
	v_pk_fma_f32 v[122:123], v[170:171], v[170:171], v[122:123]
	v_add_f32_e32 v116, v116, v117
	v_pk_fma_f32 v[122:123], v[120:121], v[120:121], v[122:123]
	v_mov_b32_e32 v173, v126
	v_add_f32_e32 v116, v116, v123
	v_add_f32_e32 v116, v122, v116
	v_mov_b32_e32 v123, v118
	v_mov_b32_e32 v118, v165
	v_add_f32_dpp v116, v116, v116 quad_perm:[1,0,3,2] row_mask:0xf bank_mask:0xf bound_ctrl:1
	v_mov_b32_e32 v126, v125
	v_mov_b32_e32 v122, v164
	v_add_f32_dpp v116, v116, v116 quad_perm:[2,3,0,1] row_mask:0xf bank_mask:0xf bound_ctrl:1
	v_mov_b32_e32 v172, v124
	v_lshlrev_b32_e32 v114, 16, v109
	v_add_f32_dpp v116, v116, v116 row_half_mirror row_mask:0xf bank_mask:0xf bound_ctrl:1
	v_and_b32_e32 v115, 0xffff0000, v109
	v_lshlrev_b32_e32 v112, 16, v108
	v_add_f32_dpp v116, v116, v116 row_mirror row_mask:0xf bank_mask:0xf bound_ctrl:1
	v_and_b32_e32 v113, 0xffff0000, v108
	v_readlane_b32 s6, v116, 16
	v_readlane_b32 s7, v116, 48
	v_readlane_b32 s4, v116, 0
	v_readlane_b32 s5, v116, 32
	v_mov_b32_e32 v116, s6
	v_mov_b32_e32 v117, s7
	v_pk_add_f32 v[116:117], s[4:5], v[116:117]
	v_lshlrev_b32_e32 v108, 16, v110
	v_add_f32_e32 v116, v116, v117
	v_fmamk_f32 v116, v116, 0x3a800000, v137
	v_cmp_gt_f32_e32 vcc, s94, v116
	v_mul_f32_e32 v117, 0x4b800000, v116
	v_and_b32_e32 v109, 0xffff0000, v110
	v_cndmask_b32_e32 v116, v116, v117, vcc
	v_rsq_f32_e32 v116, v116
	v_lshlrev_b32_e32 v110, 16, v111
	v_and_b32_e32 v111, 0xffff0000, v111
	v_mul_f32_e32 v117, 0x45800000, v116
	v_cndmask_b32_e32 v116, v116, v117, vcc
	v_pk_mul_f32 v[118:119], v[116:117], v[118:119] op_sel_hi:[0,1]
	v_pk_mul_f32 v[118:119], v[2:3], v[118:119]
	v_pk_mul_f32 v[124:125], v[116:117], v[126:127] op_sel_hi:[0,1]
	v_pk_fma_f32 v[126:127], v[62:63], v[118:119], v[154:155]
	v_mov_b32_e32 v118, v171
	v_mov_b32_e32 v119, v121
	v_pk_mul_f32 v[122:123], v[116:117], v[122:123] op_sel_hi:[0,1]
	v_pk_mul_f32 v[118:119], v[116:117], v[118:119] op_sel_hi:[0,1]
	v_pk_mul_f32 v[122:123], v[6:7], v[122:123]
	v_pk_mul_f32 v[124:125], v[0:1], v[124:125]
	v_pk_mul_f32 v[118:119], v[14:15], v[118:119]
	v_mov_b32_e32 v171, v120
	v_pk_fma_f32 v[122:123], v[58:59], v[122:123], v[150:151]
	v_pk_fma_f32 v[124:125], v[64:65], v[124:125], v[152:153]
	v_mov_b32_e32 v150, v167
	v_mov_b32_e32 v151, v169
	v_pk_fma_f32 v[152:153], v[66:67], v[118:119], v[158:159]
	v_pk_mul_f32 v[118:119], v[116:117], v[170:171] op_sel_hi:[0,1]
	v_mov_b32_e32 v167, v168
	v_pk_mul_f32 v[172:173], v[116:117], v[172:173] op_sel_hi:[0,1]
	v_pk_mul_f32 v[150:151], v[116:117], v[150:151] op_sel_hi:[0,1]
	v_pk_mul_f32 v[116:117], v[116:117], v[166:167] op_sel_hi:[0,1]
	v_pk_mul_f32 v[118:119], v[10:11], v[118:119]
	v_pk_mul_f32 v[172:173], v[4:5], v[172:173]
	v_pk_mul_f32 v[116:117], v[8:9], v[116:117]
	v_pk_fma_f32 v[120:121], v[70:71], v[118:119], v[162:163]
	v_cvt_pk_bf16_f32 v118, v124, v125
	v_cvt_pk_bf16_f32 v119, v126, v127
	v_pk_fma_f32 v[130:131], v[60:61], v[172:173], v[130:131]
	v_pk_mul_f32 v[150:151], v[12:13], v[150:151]
	v_pk_fma_f32 v[154:155], v[72:73], v[116:117], v[160:161]
	v_cvt_pk_bf16_f32 v116, v130, v131
	v_cvt_pk_bf16_f32 v117, v122, v123
	s_cmp_lg_u32 s97, 0
	s_cbranch_scc1 .Lr1086_sc1_0
	global_store_dwordx4 v[128:129], v[116:119], off
	s_branch .Lr1086_done_0

.Lr1086_done_0:
	v_pk_fma_f32 v[150:151], v[68:69], v[150:151], v[156:157]
	v_cvt_pk_bf16_f32 v118, v154, v155
	v_cvt_pk_bf16_f32 v119, v120, v121
	v_cvt_pk_bf16_f32 v116, v150, v151
	v_cvt_pk_bf16_f32 v117, v152, v153
	s_cmp_lg_u32 s97, 0
	s_cbranch_scc1 .Lr1086_sc1_1
	global_store_dwordx4 v[128:129], v[116:119], off offset:1024
	s_branch .Lr1086_done_1

.Lr1086_done_1:
	v_mov_b32_e32 v128, v155
	v_mov_b32_e32 v129, v151
	v_mov_b32_e32 v118, v131
	v_mov_b32_e32 v119, v125
	v_mov_b32_e32 v116, v130
	v_mov_b32_e32 v117, v124
	v_pk_mul_f32 v[118:119], v[118:119], v[118:119]
	v_pk_mul_f32 v[128:129], v[128:129], v[128:129]
	v_pk_fma_f32 v[116:117], v[116:117], v[116:117], v[118:119]
	v_mov_b32_e32 v118, v122
	v_mov_b32_e32 v119, v126
	v_pk_fma_f32 v[116:117], v[118:119], v[118:119], v[116:117]
	v_mov_b32_e32 v118, v123
	v_mov_b32_e32 v119, v127
	v_pk_fma_f32 v[116:117], v[118:119], v[118:119], v[116:117]
	v_mov_b32_e32 v118, v154
	v_mov_b32_e32 v119, v150
	v_pk_fma_f32 v[118:119], v[118:119], v[118:119], v[128:129]
	v_mov_b32_e32 v128, v120
	v_mov_b32_e32 v129, v152
	v_pk_fma_f32 v[118:119], v[128:129], v[128:129], v[118:119]
	v_mov_b32_e32 v128, v121
	v_mov_b32_e32 v129, v153
	v_pk_fma_f32 v[118:119], v[128:129], v[128:129], v[118:119]
	v_add_f32_e32 v116, v116, v117
	v_add_f32_e32 v116, v119, v116
	v_add_f32_e32 v116, v118, v116
	s_nop 0
	v_add_f32_dpp v116, v116, v116 quad_perm:[1,0,3,2] row_mask:0xf bank_mask:0xf bound_ctrl:1
	s_nop 1
	v_add_f32_dpp v116, v116, v116 quad_perm:[2,3,0,1] row_mask:0xf bank_mask:0xf bound_ctrl:1
	s_nop 1
	v_add_f32_dpp v116, v116, v116 row_half_mirror row_mask:0xf bank_mask:0xf bound_ctrl:1
	s_nop 1
	v_add_f32_dpp v116, v116, v116 row_mirror row_mask:0xf bank_mask:0xf bound_ctrl:1
	s_nop 0
	v_readlane_b32 s6, v116, 16
	v_readlane_b32 s7, v116, 48
	v_readlane_b32 s4, v116, 0
	v_readlane_b32 s5, v116, 32
	v_mov_b32_e32 v116, s6
	v_mov_b32_e32 v117, s7
	v_pk_add_f32 v[116:117], s[4:5], v[116:117]
	s_nop 0
	v_add_f32_e32 v116, v116, v117
	v_fmamk_f32 v116, v116, 0x3a800000, v137
	v_cmp_gt_f32_e32 vcc, s94, v116
	v_mul_f32_e32 v117, 0x4b800000, v116
	s_nop 0
	v_cndmask_b32_e32 v116, v116, v117, vcc
	v_rsq_f32_e32 v116, v116
	s_nop 0
	v_mul_f32_e32 v117, 0x45800000, v116
	v_cndmask_b32_e32 v116, v116, v117, vcc
	v_pk_mul_f32 v[118:119], v[122:123], v[116:117] op_sel_hi:[1,0]
	v_pk_mul_f32 v[122:123], v[130:131], v[116:117] op_sel_hi:[1,0]
	v_pk_mul_f32 v[118:119], v[30:31], v[118:119]
	v_pk_mul_f32 v[126:127], v[126:127], v[116:117] op_sel_hi:[1,0]
	v_pk_mul_f32 v[124:125], v[124:125], v[116:117] op_sel_hi:[1,0]
	v_pk_mul_f32 v[128:129], v[152:153], v[116:117] op_sel_hi:[1,0]
	v_pk_mul_f32 v[130:131], v[150:151], v[116:117] op_sel_hi:[1,0]
	v_pk_mul_f32 v[120:121], v[120:121], v[116:117] op_sel_hi:[1,0]
	v_pk_mul_f32 v[116:117], v[154:155], v[116:117] op_sel_hi:[1,0]
	v_pk_fma_f32 v[118:119], v[74:75], v[118:119], v[22:23]
	v_pk_mul_f32 v[124:125], v[24:25], v[124:125]
	v_pk_mul_f32 v[126:127], v[26:27], v[126:127]
	v_pk_mul_f32 v[116:117], v[40:41], v[116:117]
	v_pk_mul_f32 v[122:123], v[28:29], v[122:123]
	v_pk_fma_f32 v[126:127], v[78:79], v[126:127], v[18:19]
	v_pk_fma_f32 v[124:125], v[80:81], v[124:125], v[16:17]
	v_pk_mul_f32 v[120:121], v[42:43], v[120:121]
	v_pk_fma_f32 v[150:151], v[88:89], v[116:117], v[32:33]
	v_cvt_pk_bf16_f32 v117, v118, v119
	v_cvt_pk_bf16_f32 v118, v124, v125
	v_cvt_pk_bf16_f32 v119, v126, v127
	v_pk_fma_f32 v[122:123], v[76:77], v[122:123], v[20:21]
	v_pk_mul_f32 v[130:131], v[44:45], v[130:131]
	v_pk_mul_f32 v[128:129], v[46:47], v[128:129]
	v_pk_fma_f32 v[120:121], v[86:87], v[120:121], v[34:35]
	v_cvt_pk_bf16_f32 v116, v122, v123
	s_cmp_lg_u32 s97, 0
	s_cbranch_scc1 .Lr1086_sc1_2
	global_store_dwordx4 v[94:95], v[116:119], off
	s_branch .Lr1086_done_2

.Lr1086_done_2:
	v_pk_fma_f32 v[128:129], v[82:83], v[128:129], v[38:39]
	v_pk_fma_f32 v[130:131], v[84:85], v[130:131], v[36:37]
	v_cvt_pk_bf16_f32 v118, v150, v151
	v_cvt_pk_bf16_f32 v119, v120, v121
	v_cvt_pk_bf16_f32 v117, v128, v129
	s_waitcnt vmcnt(4)
	v_lshlrev_b32_e32 v120, 16, v53
	v_cvt_pk_bf16_f32 v116, v130, v131
	s_cmp_lg_u32 s97, 0
	s_cbranch_scc1 .Lr1086_sc1_3
	global_store_dwordx4 v[94:95], v[116:119], off offset:1024
	s_branch .Lr1086_done_3

.Lr1086_done_3:
	s_waitcnt vmcnt(4)
	v_and_b32_e32 v125, 0xffff0000, v48
	v_and_b32_e32 v124, 0xffff0000, v50
	v_and_b32_e32 v119, 0xffff0000, v54
	v_and_b32_e32 v118, 0xffff0000, v52
	v_lshlrev_b32_e32 v117, 16, v54
	v_lshlrev_b32_e32 v116, 16, v52
	v_and_b32_e32 v54, 0xffff0000, v53
	v_pk_mul_f32 v[52:53], v[118:119], v[118:119]
	v_lshlrev_b32_e32 v121, 16, v55
	v_pk_fma_f32 v[52:53], v[116:117], v[116:117], v[52:53]
	v_lshlrev_b32_e32 v123, 16, v48
	v_lshlrev_b32_e32 v122, 16, v50
	v_lshlrev_b32_e32 v126, 16, v51
	v_and_b32_e32 v48, 0xffff0000, v51
	v_pk_mul_f32 v[50:51], v[124:125], v[124:125]
	v_and_b32_e32 v55, 0xffff0000, v55
	v_pk_fma_f32 v[52:53], v[120:121], v[120:121], v[52:53]
	v_lshlrev_b32_e32 v127, 16, v49
	v_pk_fma_f32 v[50:51], v[122:123], v[122:123], v[50:51]
	v_pk_fma_f32 v[52:53], v[54:55], v[54:55], v[52:53]
	v_and_b32_e32 v49, 0xffff0000, v49
	v_pk_fma_f32 v[50:51], v[126:127], v[126:127], v[50:51]
	v_add_f32_e32 v52, v52, v53
	v_pk_fma_f32 v[50:51], v[48:49], v[48:49], v[50:51]
	v_mov_b32_e32 v53, v54
	v_add_f32_e32 v51, v52, v51
	v_add_f32_e32 v50, v50, v51
	v_mov_b32_e32 v52, v120
	v_mov_b32_e32 v129, v118
	v_add_f32_dpp v50, v50, v50 quad_perm:[1,0,3,2] row_mask:0xf bank_mask:0xf bound_ctrl:1
	v_mov_b32_e32 v54, v121
	v_mov_b32_e32 v118, v117
	v_add_f32_dpp v50, v50, v50 quad_perm:[2,3,0,1] row_mask:0xf bank_mask:0xf bound_ctrl:1
	v_mov_b32_e32 v128, v116
	v_lshl_add_u64 v[94:95], v[94:95], 0, s[30:31]
	v_add_f32_dpp v50, v50, v50 row_half_mirror row_mask:0xf bank_mask:0xf bound_ctrl:1
	s_nop 1
	v_add_f32_dpp v50, v50, v50 row_mirror row_mask:0xf bank_mask:0xf bound_ctrl:1
	s_nop 0
	v_readlane_b32 s6, v50, 16
	v_readlane_b32 s7, v50, 48
	v_readlane_b32 s4, v50, 0
	v_readlane_b32 s5, v50, 32
	v_mov_b32_e32 v50, s6
	v_mov_b32_e32 v51, s7
	v_pk_add_f32 v[50:51], s[4:5], v[50:51]
	s_nop 0
	v_add_f32_e32 v50, v50, v51
	v_fmamk_f32 v50, v50, 0x3a800000, v137
	v_cmp_gt_f32_e32 vcc, s94, v50
	v_mul_f32_e32 v51, 0x4b800000, v50
	s_nop 0
	v_cndmask_b32_e32 v50, v50, v51, vcc
	v_rsq_f32_e32 v50, v50
	s_nop 0
	v_mul_f32_e32 v51, 0x45800000, v50
	v_cndmask_b32_e32 v50, v50, v51, vcc
	v_pk_mul_f32 v[52:53], v[50:51], v[52:53] op_sel_hi:[0,1]
	v_pk_mul_f32 v[52:53], v[6:7], v[52:53]
	v_pk_mul_f32 v[54:55], v[50:51], v[54:55] op_sel_hi:[0,1]
	v_pk_fma_f32 v[52:53], v[58:59], v[52:53], v[114:115]
	v_pk_mul_f32 v[114:115], v[50:51], v[118:119] op_sel_hi:[0,1]
	v_pk_mul_f32 v[114:115], v[0:1], v[114:115]
	v_pk_mul_f32 v[54:55], v[2:3], v[54:55]
	v_pk_fma_f32 v[108:109], v[64:65], v[114:115], v[108:109]
	v_pk_fma_f32 v[54:55], v[62:63], v[54:55], v[110:111]
	v_mov_b32_e32 v110, v127
	v_mov_b32_e32 v111, v49
	v_mov_b32_e32 v114, v123
	v_mov_b32_e32 v115, v125
	v_mov_b32_e32 v127, v48
	v_mov_b32_e32 v123, v124
	v_pk_mul_f32 v[128:129], v[50:51], v[128:129] op_sel_hi:[0,1]
	v_pk_mul_f32 v[110:111], v[50:51], v[110:111] op_sel_hi:[0,1]
	v_pk_mul_f32 v[114:115], v[50:51], v[114:115] op_sel_hi:[0,1]
	v_pk_mul_f32 v[48:49], v[50:51], v[126:127] op_sel_hi:[0,1]
	v_pk_mul_f32 v[50:51], v[50:51], v[122:123] op_sel_hi:[0,1]
	v_pk_mul_f32 v[50:51], v[8:9], v[50:51]
	v_pk_mul_f32 v[128:129], v[4:5], v[128:129]
	v_pk_mul_f32 v[48:49], v[10:11], v[48:49]
	v_pk_fma_f32 v[100:101], v[72:73], v[50:51], v[100:101]
	v_cvt_pk_bf16_f32 v50, v108, v109
	v_cvt_pk_bf16_f32 v51, v54, v55
	v_pk_fma_f32 v[112:113], v[60:61], v[128:129], v[112:113]
	v_pk_mul_f32 v[114:115], v[12:13], v[114:115]
	v_pk_mul_f32 v[110:111], v[14:15], v[110:111]
	v_pk_fma_f32 v[102:103], v[70:71], v[48:49], v[102:103]
	v_cvt_pk_bf16_f32 v48, v112, v113
	v_cvt_pk_bf16_f32 v49, v52, v53
	s_cmp_lg_u32 s97, 0
	s_cbranch_scc1 .Lr1086_sc1_4
	global_store_dwordx4 v[98:99], v[48:51], off
	s_branch .Lr1086_done_4
.Lr1086_sc1_4:
	global_store_dwordx4 v[98:99], v[48:51], off sc1
.Lr1086_done_4:
	v_pk_fma_f32 v[106:107], v[66:67], v[110:111], v[106:107]
	v_pk_fma_f32 v[104:105], v[68:69], v[114:115], v[104:105]
	v_cvt_pk_bf16_f32 v50, v100, v101
	v_cvt_pk_bf16_f32 v51, v102, v103
	v_cvt_pk_bf16_f32 v49, v106, v107
	s_nop 0
	v_cvt_pk_bf16_f32 v48, v104, v105
	s_cmp_lg_u32 s97, 0
	s_cbranch_scc1 .Lr1086_sc1_5
	global_store_dwordx4 v[98:99], v[48:51], off offset:1024
	s_branch .Lr1086_done_5
.Lr1086_sc1_5:
	global_store_dwordx4 v[98:99], v[48:51], off offset:1024 sc1
.Lr1086_done_5:
	v_mov_b32_e32 v98, v101
	v_mov_b32_e32 v99, v105
	v_mov_b32_e32 v50, v113
	v_mov_b32_e32 v51, v109
	v_mov_b32_e32 v48, v112
	v_mov_b32_e32 v49, v108
	v_pk_mul_f32 v[50:51], v[50:51], v[50:51]
	v_pk_mul_f32 v[98:99], v[98:99], v[98:99]
	v_pk_fma_f32 v[48:49], v[48:49], v[48:49], v[50:51]
	v_mov_b32_e32 v50, v52
	v_mov_b32_e32 v51, v54
	v_pk_fma_f32 v[48:49], v[50:51], v[50:51], v[48:49]
	v_mov_b32_e32 v50, v53
	v_mov_b32_e32 v51, v55
	v_pk_fma_f32 v[48:49], v[50:51], v[50:51], v[48:49]
	v_mov_b32_e32 v50, v100
	v_mov_b32_e32 v51, v104
	v_pk_fma_f32 v[50:51], v[50:51], v[50:51], v[98:99]
	v_mov_b32_e32 v98, v102
	v_mov_b32_e32 v99, v106
	v_pk_fma_f32 v[50:51], v[98:99], v[98:99], v[50:51]
	v_mov_b32_e32 v98, v103
	v_mov_b32_e32 v99, v107
	v_pk_fma_f32 v[50:51], v[98:99], v[98:99], v[50:51]
	v_add_f32_e32 v48, v48, v49
	v_add_f32_e32 v48, v51, v48
	v_add_f32_e32 v48, v50, v48
	s_nop 1
	v_add_f32_dpp v48, v48, v48 quad_perm:[1,0,3,2] row_mask:0xf bank_mask:0xf bound_ctrl:1
	s_nop 1
	v_add_f32_dpp v48, v48, v48 quad_perm:[2,3,0,1] row_mask:0xf bank_mask:0xf bound_ctrl:1
	s_nop 1
	v_add_f32_dpp v48, v48, v48 row_half_mirror row_mask:0xf bank_mask:0xf bound_ctrl:1
	s_nop 1
	v_add_f32_dpp v48, v48, v48 row_mirror row_mask:0xf bank_mask:0xf bound_ctrl:1
	s_nop 0
	v_readlane_b32 s6, v48, 16
	v_readlane_b32 s7, v48, 48
	v_readlane_b32 s4, v48, 0
	v_readlane_b32 s5, v48, 32
	v_mov_b32_e32 v48, s6
	v_mov_b32_e32 v49, s7
	v_pk_add_f32 v[48:49], s[4:5], v[48:49]
	s_nop 0
	v_add_f32_e32 v48, v48, v49
	v_fmamk_f32 v48, v48, 0x3a800000, v137
	v_cmp_gt_f32_e32 vcc, s94, v48
	v_mul_f32_e32 v49, 0x4b800000, v48
	s_nop 0
	v_cndmask_b32_e32 v48, v48, v49, vcc
	v_rsq_f32_e32 v48, v48
	s_nop 0
	v_mul_f32_e32 v49, 0x45800000, v48
	v_cndmask_b32_e32 v48, v48, v49, vcc
	v_pk_mul_f32 v[50:51], v[52:53], v[48:49] op_sel_hi:[1,0]
	v_pk_mul_f32 v[52:53], v[112:113], v[48:49] op_sel_hi:[1,0]
	v_pk_mul_f32 v[50:51], v[30:31], v[50:51]
	v_pk_mul_f32 v[54:55], v[54:55], v[48:49] op_sel_hi:[1,0]
	v_pk_mul_f32 v[98:99], v[108:109], v[48:49] op_sel_hi:[1,0]
	v_pk_mul_f32 v[106:107], v[106:107], v[48:49] op_sel_hi:[1,0]
	v_pk_mul_f32 v[104:105], v[104:105], v[48:49] op_sel_hi:[1,0]
	v_pk_mul_f32 v[102:103], v[102:103], v[48:49] op_sel_hi:[1,0]
	v_pk_mul_f32 v[48:49], v[100:101], v[48:49] op_sel_hi:[1,0]
	v_pk_mul_f32 v[52:53], v[28:29], v[52:53]
	v_pk_fma_f32 v[50:51], v[74:75], v[50:51], v[22:23]
	v_pk_mul_f32 v[98:99], v[24:25], v[98:99]
	v_pk_mul_f32 v[54:55], v[26:27], v[54:55]
	v_pk_mul_f32 v[48:49], v[40:41], v[48:49]
	v_pk_fma_f32 v[52:53], v[76:77], v[52:53], v[20:21]
	v_pk_fma_f32 v[54:55], v[78:79], v[54:55], v[18:19]
	v_pk_fma_f32 v[98:99], v[80:81], v[98:99], v[16:17]
	v_pk_mul_f32 v[104:105], v[44:45], v[104:105]
	v_pk_mul_f32 v[106:107], v[46:47], v[106:107]
	v_pk_mul_f32 v[100:101], v[42:43], v[102:103]
	v_pk_fma_f32 v[102:103], v[88:89], v[48:49], v[32:33]
	v_cvt_pk_bf16_f32 v48, v52, v53
	v_cvt_pk_bf16_f32 v49, v50, v51
	v_cvt_pk_bf16_f32 v50, v98, v99
	v_cvt_pk_bf16_f32 v51, v54, v55
	v_pk_fma_f32 v[106:107], v[82:83], v[106:107], v[38:39]
	v_pk_fma_f32 v[104:105], v[84:85], v[104:105], v[36:37]
	v_pk_fma_f32 v[100:101], v[86:87], v[100:101], v[34:35]
	s_cmp_lg_u32 s97, 0
	s_cbranch_scc1 .Lr1086_sc1_6
	global_store_dwordx4 v[96:97], v[48:51], off
	s_branch .Lr1086_done_6
.Lr1086_sc1_6:
	global_store_dwordx4 v[96:97], v[48:51], off sc1
.Lr1086_done_6:
	s_nop 1
	v_cvt_pk_bf16_f32 v48, v104, v105
	v_cvt_pk_bf16_f32 v49, v106, v107
	v_cvt_pk_bf16_f32 v50, v102, v103
	v_cvt_pk_bf16_f32 v51, v100, v101
	s_cmp_lg_u32 s97, 0
	s_cbranch_scc1 .Lr1086_sc1_7
	global_store_dwordx4 v[96:97], v[48:51], off offset:1024
	s_branch .Lr1086_done_7
.Lr1086_sc1_7:
	global_store_dwordx4 v[96:97], v[48:51], off offset:1024 sc1
.Lr1086_done_7:
	s_add_u32 s2, s2, 2
	s_addc_u32 s3, s3, 0
	s_cmp_lt_i32 s2, s8
	s_cbranch_scc1 .LBB0_1086
